# ffn2-up weight conversion beside rwkv_apply: plain stores instead of nt stores
# speedup vs baseline: 1.0040x; 1.0040x over previous
.Lcv_procA_p7up:
	s_lshr_b32 s10, s0, 5
	s_mul_i32 s10, s10, 0x1746
	s_lshr_b32 s10, s10, 16
	s_mul_i32 s11, s10, 352
	s_sub_u32 s11, s0, s11
	ds_write2_b32 v44, v64, v65 offset1:1
	ds_write2_b32 v44, v66, v67 offset0:2 offset1:3
	ds_write2_b32 v45, v68, v69 offset1:1
	ds_write2_b32 v45, v70, v71 offset0:2 offset1:3
	ds_write2_b32 v46, v72, v73 offset1:1
	ds_write2_b32 v46, v74, v75 offset0:2 offset1:3
	ds_write2_b32 v47, v76, v77 offset1:1
	ds_write2_b32 v47, v78, v79 offset0:2 offset1:3
	ds_write2_b32 v48, v80, v81 offset1:1
	ds_write2_b32 v48, v82, v83 offset0:2 offset1:3
	ds_write2_b32 v49, v84, v85 offset1:1
	ds_write2_b32 v49, v86, v87 offset0:2 offset1:3
	ds_write2_b32 v50, v88, v89 offset1:1
	ds_write2_b32 v50, v90, v91 offset0:2 offset1:3
	ds_write2_b32 v51, v92, v93 offset1:1
	ds_write2_b32 v51, v94, v95 offset0:2 offset1:3
	s_mul_i32 s5, s11, 0x20000
	s_lshl_b32 s6, s10, 7
	s_add_u32 s5, s5, s6
	s_add_u32 s14, s50, s5
	s_addc_u32 s15, s51, 0
	s_waitcnt lgkmcnt(0)
	ds_read2_b32 v[8:9], v52 offset0:0 offset1:33
	ds_read2_b32 v[10:11], v52 offset0:66 offset1:99
	ds_read2_b32 v[12:13], v52 offset0:132 offset1:165
	ds_read2_b32 v[14:15], v52 offset0:198 offset1:231
	ds_read2_b32 v[16:17], v52 offset0:8 offset1:41
	ds_read2_b32 v[18:19], v52 offset0:74 offset1:107
	ds_read2_b32 v[20:21], v52 offset0:140 offset1:173
	ds_read2_b32 v[22:23], v52 offset0:206 offset1:239
	ds_read2_b32 v[24:25], v52 offset0:16 offset1:49
	ds_read2_b32 v[26:27], v52 offset0:82 offset1:115
	ds_read2_b32 v[28:29], v52 offset0:148 offset1:181
	ds_read2_b32 v[30:31], v52 offset0:214 offset1:247
	ds_read2_b32 v[32:33], v52 offset0:24 offset1:57
	ds_read2_b32 v[34:35], v52 offset0:90 offset1:123
	ds_read2_b32 v[36:37], v52 offset0:156 offset1:189
	ds_read2_b32 v[38:39], v52 offset0:222 offset1:255
	s_waitcnt lgkmcnt(12)
	v_cvt_pk_bf16_f32 v148, v8, v9
	v_cvt_pk_bf16_f32 v149, v10, v11
	v_cvt_pk_bf16_f32 v150, v12, v13
	v_cvt_pk_bf16_f32 v151, v14, v15
	global_store_dwordx4 v54, v[148:151], s[14:15]
	s_add_u32 s14, s14, 0x8000
	s_addc_u32 s15, s15, 0
	s_waitcnt lgkmcnt(8)
	v_cvt_pk_bf16_f32 v152, v16, v17
	v_cvt_pk_bf16_f32 v153, v18, v19
	v_cvt_pk_bf16_f32 v154, v20, v21
	v_cvt_pk_bf16_f32 v155, v22, v23
	global_store_dwordx4 v54, v[152:155], s[14:15]
	s_add_u32 s14, s14, 0x8000
	s_addc_u32 s15, s15, 0
	s_waitcnt lgkmcnt(4)
	v_cvt_pk_bf16_f32 v156, v24, v25
	v_cvt_pk_bf16_f32 v157, v26, v27
	v_cvt_pk_bf16_f32 v158, v28, v29
	v_cvt_pk_bf16_f32 v159, v30, v31
	global_store_dwordx4 v54, v[156:159], s[14:15]
	s_add_u32 s14, s14, 0x8000
	s_addc_u32 s15, s15, 0
	s_waitcnt lgkmcnt(0)
	v_cvt_pk_bf16_f32 v160, v32, v33
	v_cvt_pk_bf16_f32 v161, v34, v35
	v_cvt_pk_bf16_f32 v162, v36, v37
	v_cvt_pk_bf16_f32 v163, v38, v39
	global_store_dwordx4 v54, v[160:163], s[14:15]
	s_cmp_ge_u32 s1, 0x2c00
	s_cbranch_scc1 .Lcv_done_p7up
	s_add_u32 s0, s1, s9
	s_cmp_ge_u32 s0, 0x2c00
	s_cbranch_scc1 .Lcv_tailB_p7up
	s_lshr_b32 s10, s0, 5
	s_mul_i32 s10, s10, 0x1746
	s_lshr_b32 s10, s10, 16
	s_mul_i32 s11, s10, 352
	s_sub_u32 s11, s0, s11
	s_lshl_b32 s5, s11, 5
	s_lshr_b32 s6, s5, 8
	s_lshl_b32 s6, s6, 7
	s_and_b32 s7, s5, 0x7f
	s_add_u32 s6, s6, s7
	s_bitcmp1_b32 s5, 7
	s_mov_b32 s5, s6
	s_cselect_b32 s12, s64, s62
	s_cselect_b32 s13, s65, s63
	s_mul_i32 s6, s10, 0x160000
	s_lshl_b32 s5, s5, 2
	s_add_u32 s6, s6, s5
	s_add_u32 s12, s12, s6
	s_addc_u32 s13, s13, 0
	global_load_dwordx4 v[64:67], v53, s[12:13] nt
	s_add_u32 s12, s12, 0x2c000
	s_addc_u32 s13, s13, 0
	global_load_dwordx4 v[68:71], v53, s[12:13] nt
	s_add_u32 s12, s12, 0x2c000
	s_addc_u32 s13, s13, 0
	global_load_dwordx4 v[72:75], v53, s[12:13] nt
	s_add_u32 s12, s12, 0x2c000
	s_addc_u32 s13, s13, 0
	global_load_dwordx4 v[76:79], v53, s[12:13] nt
	s_add_u32 s12, s12, 0x2c000
	s_addc_u32 s13, s13, 0
	global_load_dwordx4 v[80:83], v53, s[12:13] nt
	s_add_u32 s12, s12, 0x2c000
	s_addc_u32 s13, s13, 0
	global_load_dwordx4 v[84:87], v53, s[12:13] nt
	s_add_u32 s12, s12, 0x2c000
	s_addc_u32 s13, s13, 0
	global_load_dwordx4 v[88:91], v53, s[12:13] nt
	s_add_u32 s12, s12, 0x2c000
	s_addc_u32 s13, s13, 0
	global_load_dwordx4 v[92:95], v53, s[12:13] nt
	s_waitcnt vmcnt(12)
	s_branch .Lcv_procB_p7up

.Lcv_procB_p7up:
	s_lshr_b32 s10, s1, 5
	s_mul_i32 s10, s10, 0x1746
	s_lshr_b32 s10, s10, 16
	s_mul_i32 s11, s10, 352
	s_sub_u32 s11, s1, s11
	ds_write2_b32 v44, v96, v97 offset1:1
	ds_write2_b32 v44, v98, v99 offset0:2 offset1:3
	ds_write2_b32 v45, v100, v101 offset1:1
	ds_write2_b32 v45, v102, v103 offset0:2 offset1:3
	ds_write2_b32 v46, v104, v105 offset1:1
	ds_write2_b32 v46, v106, v107 offset0:2 offset1:3
	ds_write2_b32 v47, v108, v109 offset1:1
	ds_write2_b32 v47, v110, v111 offset0:2 offset1:3
	ds_write2_b32 v48, v112, v113 offset1:1
	ds_write2_b32 v48, v114, v115 offset0:2 offset1:3
	ds_write2_b32 v49, v116, v117 offset1:1
	ds_write2_b32 v49, v118, v119 offset0:2 offset1:3
	ds_write2_b32 v50, v120, v121 offset1:1
	ds_write2_b32 v50, v122, v123 offset0:2 offset1:3
	ds_write2_b32 v51, v124, v125 offset1:1
	ds_write2_b32 v51, v126, v127 offset0:2 offset1:3
	s_mul_i32 s5, s11, 0x20000
	s_lshl_b32 s6, s10, 7
	s_add_u32 s5, s5, s6
	s_add_u32 s14, s50, s5
	s_addc_u32 s15, s51, 0
	s_waitcnt lgkmcnt(0)
	ds_read2_b32 v[8:9], v52 offset0:0 offset1:33
	ds_read2_b32 v[10:11], v52 offset0:66 offset1:99
	ds_read2_b32 v[12:13], v52 offset0:132 offset1:165
	ds_read2_b32 v[14:15], v52 offset0:198 offset1:231
	ds_read2_b32 v[16:17], v52 offset0:8 offset1:41
	ds_read2_b32 v[18:19], v52 offset0:74 offset1:107
	ds_read2_b32 v[20:21], v52 offset0:140 offset1:173
	ds_read2_b32 v[22:23], v52 offset0:206 offset1:239
	ds_read2_b32 v[24:25], v52 offset0:16 offset1:49
	ds_read2_b32 v[26:27], v52 offset0:82 offset1:115
	ds_read2_b32 v[28:29], v52 offset0:148 offset1:181
	ds_read2_b32 v[30:31], v52 offset0:214 offset1:247
	ds_read2_b32 v[32:33], v52 offset0:24 offset1:57
	ds_read2_b32 v[34:35], v52 offset0:90 offset1:123
	ds_read2_b32 v[36:37], v52 offset0:156 offset1:189
	ds_read2_b32 v[38:39], v52 offset0:222 offset1:255
	s_waitcnt lgkmcnt(12)
	v_cvt_pk_bf16_f32 v148, v8, v9
	v_cvt_pk_bf16_f32 v149, v10, v11
	v_cvt_pk_bf16_f32 v150, v12, v13
	v_cvt_pk_bf16_f32 v151, v14, v15
	global_store_dwordx4 v54, v[148:151], s[14:15]
	s_add_u32 s14, s14, 0x8000
	s_addc_u32 s15, s15, 0
	s_waitcnt lgkmcnt(8)
	v_cvt_pk_bf16_f32 v152, v16, v17
	v_cvt_pk_bf16_f32 v153, v18, v19
	v_cvt_pk_bf16_f32 v154, v20, v21
	v_cvt_pk_bf16_f32 v155, v22, v23
	global_store_dwordx4 v54, v[152:155], s[14:15]
	s_add_u32 s14, s14, 0x8000
	s_addc_u32 s15, s15, 0
	s_waitcnt lgkmcnt(4)
	v_cvt_pk_bf16_f32 v156, v24, v25
	v_cvt_pk_bf16_f32 v157, v26, v27
	v_cvt_pk_bf16_f32 v158, v28, v29
	v_cvt_pk_bf16_f32 v159, v30, v31
	global_store_dwordx4 v54, v[156:159], s[14:15]
	s_add_u32 s14, s14, 0x8000
	s_addc_u32 s15, s15, 0
	s_waitcnt lgkmcnt(0)
	v_cvt_pk_bf16_f32 v160, v32, v33
	v_cvt_pk_bf16_f32 v161, v34, v35
	v_cvt_pk_bf16_f32 v162, v36, v37
	v_cvt_pk_bf16_f32 v163, v38, v39
	global_store_dwordx4 v54, v[160:163], s[14:15]
	s_cmp_ge_u32 s0, 0x2c00
	s_cbranch_scc1 .Lcv_done_p7up
	s_add_u32 s1, s0, s9
	s_cmp_ge_u32 s1, 0x2c00
	s_cbranch_scc1 .Lcv_tailA_p7up
	s_lshr_b32 s10, s1, 5
	s_mul_i32 s10, s10, 0x1746
	s_lshr_b32 s10, s10, 16
	s_mul_i32 s11, s10, 352
	s_sub_u32 s11, s1, s11
	s_lshl_b32 s5, s11, 5
	s_lshr_b32 s6, s5, 8
	s_lshl_b32 s6, s6, 7
	s_and_b32 s7, s5, 0x7f
	s_add_u32 s6, s6, s7
	s_bitcmp1_b32 s5, 7
	s_mov_b32 s5, s6
	s_cselect_b32 s12, s64, s62
	s_cselect_b32 s13, s65, s63
	s_mul_i32 s6, s10, 0x160000
	s_lshl_b32 s5, s5, 2
	s_add_u32 s6, s6, s5
	s_add_u32 s12, s12, s6
	s_addc_u32 s13, s13, 0
	global_load_dwordx4 v[96:99], v53, s[12:13] nt
	s_add_u32 s12, s12, 0x2c000
	s_addc_u32 s13, s13, 0
	global_load_dwordx4 v[100:103], v53, s[12:13] nt
	s_add_u32 s12, s12, 0x2c000
	s_addc_u32 s13, s13, 0
	global_load_dwordx4 v[104:107], v53, s[12:13] nt
	s_add_u32 s12, s12, 0x2c000
	s_addc_u32 s13, s13, 0
	global_load_dwordx4 v[108:111], v53, s[12:13] nt
	s_add_u32 s12, s12, 0x2c000
	s_addc_u32 s13, s13, 0
	global_load_dwordx4 v[112:115], v53, s[12:13] nt
	s_add_u32 s12, s12, 0x2c000
	s_addc_u32 s13, s13, 0
	global_load_dwordx4 v[116:119], v53, s[12:13] nt
	s_add_u32 s12, s12, 0x2c000
	s_addc_u32 s13, s13, 0
	global_load_dwordx4 v[120:123], v53, s[12:13] nt
	s_add_u32 s12, s12, 0x2c000
	s_addc_u32 s13, s13, 0
	global_load_dwordx4 v[124:127], v53, s[12:13] nt
	s_waitcnt vmcnt(12)
	s_branch .Lcv_procA_p7up
